# static s_setprio 1 for waves 4-7 at token-mixer phase entry (one wave of each SIMD pair wins arbitration)
# speedup vs baseline: 1.0057x; 1.0057x over previous
; __global__ void __launch_bounds__(NT, 2) trunk_fwd(Args args) {
;     ...
;         if (IN(pb + 1)) for (int rep = 0; rep < (even ? REP_ATTN : 1); ++rep) {
;             if (rep) grid.sync();
;             if (even) {
;                 for (int u = bx; u < 2048; u += G) {
;                     const int rnd = u / 256, w = u % 256, x = w % 8, j = w / 8, pr = 4 * x + (rnd & 3), b = pr / 8, hh = pr % 8;
.LBB0_522:
	s_andn2_b64 vcc, exec, s[0:1]
	s_cbranch_vccnz .LBB0_754
	v_readfirstlane_b32 s0, v232
	s_nop 0
	s_lshr_b32 s0, s0, 6
	s_cmp_ge_u32 s0, 4
	s_cbranch_scc0 .Lprio_mix_done
	s_setprio 1
.Lprio_mix_done:
	s_andn2_b64 vcc, exec, s[8:9]
	s_mov_b64 s[0:1], -1
	v_readlane_b32 s37, v255, 15
	v_readlane_b32 s43, v255, 20
	s_cbranch_vccnz .LBB0_547
	v_readlane_b32 s0, v254, 6
	v_readlane_b32 s1, v254, 7
	s_andn2_b64 vcc, exec, s[0:1]
	v_readlane_b32 s27, v255, 16
	v_readlane_b32 s28, v255, 17
	v_readlane_b32 s38, v255, 18
	s_cbranch_vccnz .LBB0_546
	s_lshl_b32 s86, s89, 4
	s_lshl_b64 s[0:1], s[86:87], 2
	s_mov_b32 s10, s2
	s_branch .LBB0_527
